# LayerNorm-folded weight matrices converted by a new software-pipelined routine (dwordx4 loads, two tiles in flight, LDS-staged gain/bias, DPP/bpermute column sums) instead of the serial per-item path
# baseline (speedup 1.0000x reference)
.Lgv_begin:
	s_mov_b32 s30, s0
	v_lshrrev_b32_e32 v2, 3, v244
	v_and_b32_e32 v3, 7, v244
	v_lshlrev_b32_e32 v5, 2, v244
	s_lshl_b32 s31, s85, 14
	v_lshlrev_b32_e32 v6, 7, v2
	v_add_u32_e32 v6, s31, v6
	v_xor_b32_e32 v8, 0, v3
	v_lshl_add_u32 v21, v8, 4, v6
	v_xor_b32_e32 v8, 1, v3
	v_lshl_add_u32 v22, v8, 4, v6
	v_xor_b32_e32 v8, 2, v3
	v_lshl_add_u32 v23, v8, 4, v6
	v_xor_b32_e32 v8, 3, v3
	v_lshl_add_u32 v24, v8, 4, v6
	v_xor_b32_e32 v8, 4, v3
	v_lshl_add_u32 v25, v8, 4, v6
	v_xor_b32_e32 v8, 5, v3
	v_lshl_add_u32 v26, v8, 4, v6
	v_xor_b32_e32 v8, 6, v3
	v_lshl_add_u32 v27, v8, 4, v6
	v_xor_b32_e32 v8, 7, v3
	v_lshl_add_u32 v28, v8, 4, v6
	v_lshlrev_b32_e32 v7, 10, v3
	v_add_u32_e32 v7, s31, v7
	v_add_u32_e32 v8, 0, v2
	v_lshrrev_b32_e32 v9, 2, v8
	v_xor_b32_e32 v9, v9, v3
	v_and_b32_e32 v8, 3, v8
	v_lshl_add_u32 v8, v9, 2, v8
	v_lshl_add_u32 v29, v8, 2, v7
	v_add_u32_e32 v8, 8, v2
	v_lshrrev_b32_e32 v9, 2, v8
	v_xor_b32_e32 v9, v9, v3
	v_and_b32_e32 v8, 3, v8
	v_lshl_add_u32 v8, v9, 2, v8
	v_lshl_add_u32 v30, v8, 2, v7
	v_add_u32_e32 v8, 16, v2
	v_lshrrev_b32_e32 v9, 2, v8
	v_xor_b32_e32 v9, v9, v3
	v_and_b32_e32 v8, 3, v8
	v_lshl_add_u32 v8, v9, 2, v8
	v_lshl_add_u32 v31, v8, 2, v7
	v_add_u32_e32 v8, 24, v2
	v_lshrrev_b32_e32 v9, 2, v8
	v_xor_b32_e32 v9, v9, v3
	v_and_b32_e32 v8, 3, v8
	v_lshl_add_u32 v8, v9, 2, v8
	v_lshl_add_u32 v32, v8, 2, v7
	v_lshl_add_u32 v8, v3, 3, v2
	v_lshlrev_b32_e32 v8, 2, v8
	v_add_u32_e32 v10, s31, v8
	v_add_u32_e32 v10, 0x2000, v10
	v_lshlrev_b32_e32 v8, 5, v2
	v_add_u32_e32 v11, s31, v8
	v_add_u32_e32 v11, 0x2000, v11
	v_xor_b32_e32 v8, 8, v244
	v_lshlrev_b32_e32 v12, 2, v8
	v_xor_b32_e32 v8, 16, v244
	v_lshlrev_b32_e32 v13, 2, v8
	v_xor_b32_e32 v8, 32, v244
	v_lshlrev_b32_e32 v14, 2, v8
	v_lshlrev_b32_e32 v15, 2, v2
	v_lshlrev_b32_e32 v16, 4, v3
	v_lshlrev_b32_e32 v17, 12, v2
	v_lshl_add_u32 v17, v3, 4, v17
	v_add_u32_e32 v18, 0x8000, v17
	v_add_u32_e32 v19, 0x10000, v17
	v_add_u32_e32 v20, 0x18000, v17
	s_mov_b32 s56, 0x1010101
	s_mov_b32 s57, 0x1010101
	s_mov_b64 s[64:65], 0xff
	s_mov_b32 s59, 0xffff0000
	s_waitcnt lgkmcnt(0)
	s_cmp_lt_u32 s30, 0x4000
	s_cbranch_scc1 .Lgv1_w1
	s_cmp_lt_u32 s30, 0x5000
	s_cbranch_scc1 .Lgv1_pg
	s_cmp_lt_u32 s30, 0x5800
	s_cbranch_scc1 .Lgv1_wq
	s_cmp_lt_u32 s30, 0x5a00
	s_cbranch_scc1 .Lgv1_wk
	s_cmp_lt_u32 s30, 0x5c00
	s_cbranch_scc1 .Lgv1_wv
	s_mov_b32 s12, 0
	s_load_dwordx2 s[4:5], s[18:19], 0x98
	s_load_dwordx2 s[6:7], s[18:19], 0x100
	s_load_dwordx2 s[8:9], s[18:19], 0x108
	s_mov_b32 s10, 11
	s_mov_b32 s11, 4
	s_mov_b32 s69, 0x2d200000
	s_mov_b32 s70, 0x2e200000
	s_mov_b32 s40, 0x3000
	s_mov_b32 s71, 0
	s_mov_b32 s72, 0
	s_branch .Lgv1_common
.Lgv1_w1:
	s_lshr_b32 s15, s30, 13
	s_and_b32 s12, s30, 0x1fff
	s_load_dwordx2 s[4:5], s[18:19], 0xd0
	s_load_dwordx2 s[6:7], s[18:19], 0xc0
	s_load_dwordx2 s[8:9], s[18:19], 0xc8
	s_mov_b32 s10, 15
	s_mov_b32 s11, 8
	s_mov_b32 s73, 0x6f00000
	s_mov_b32 s69, 0x1200000
	s_mov_b32 s74, 0x19a000
	s_mov_b32 s70, 0x180000
	s_cmp_lg_u32 s15, 0
	s_cselect_b32 s69, s73, s69
	s_cselect_b32 s70, s74, s70
	s_mov_b32 s40, 0x8000
	s_lshl_b32 s71, s15, 26
	s_lshl_b32 s72, s15, 13
	s_branch .Lgv1_common
.Lgv1_pg:
	s_add_i32 s12, s30, 0xffffc000
	s_lshr_b32 s15, s12, 11
	s_and_b32 s12, s12, 0x7ff
	s_load_dwordx2 s[4:5], s[18:19], 0xf8
	s_load_dwordx2 s[6:7], s[18:19], 0xe0
	s_load_dwordx2 s[8:9], s[18:19], 0xe8
	s_mov_b32 s10, 13
	s_mov_b32 s11, 6
	s_mov_b32 s73, 0xb000000
	s_mov_b32 s69, 0x5300000
	s_mov_b32 s74, 0x1aa000
	s_mov_b32 s70, 0x190000
	s_cmp_lg_u32 s15, 0
	s_cselect_b32 s69, s73, s69
	s_cselect_b32 s70, s74, s70
	s_mov_b32 s40, 0x2000
	s_lshl_b32 s71, s15, 24
	s_lshl_b32 s72, s15, 13
	s_branch .Lgv1_common
.Lgv1_wq:
	s_add_i32 s12, s30, 0xffffb000
	s_load_dwordx2 s[4:5], s[18:19], 0xa8
	s_load_dwordx2 s[6:7], s[18:19], 0x100
	s_load_dwordx2 s[8:9], s[18:19], 0x108
	s_mov_b32 s10, 13
	s_mov_b32 s11, 6
	s_mov_b32 s69, 0x5f00000
	s_mov_b32 s70, 0x195000
	s_mov_b32 s40, 0x3000
	s_mov_b32 s71, 0
	s_mov_b32 s72, 0
	s_branch .Lgv1_common
.Lgv1_wk:
	s_add_i32 s12, s30, 0xffffa800
	s_load_dwordx2 s[4:5], s[18:19], 0x98
	s_load_dwordx2 s[6:7], s[18:19], 0x100
	s_load_dwordx2 s[8:9], s[18:19], 0x108
	s_mov_b32 s10, 11
	s_mov_b32 s11, 4
	s_mov_b32 s69, 0x5b00000
	s_mov_b32 s70, 0x194000
	s_mov_b32 s40, 0x3000
	s_mov_b32 s71, 0
	s_mov_b32 s72, 0
	s_branch .Lgv1_common
.Lgv1_wv:
	s_add_i32 s12, s30, 0xffffa600
	s_load_dwordx2 s[4:5], s[18:19], 0xa0
	s_load_dwordx2 s[6:7], s[18:19], 0x100
	s_load_dwordx2 s[8:9], s[18:19], 0x108
	s_mov_b32 s10, 11
	s_mov_b32 s11, 4
	s_mov_b32 s69, 0x5d00000
	s_mov_b32 s70, 0x194800
	s_mov_b32 s40, 0x3000
	s_mov_b32 s71, 0
	s_mov_b32 s72, 0
.Lgv1_common:
	s_lshr_b32 s13, s12, s11
	s_lshl_b32 s15, s13, s11
	s_sub_i32 s14, s12, s15
	s_add_i32 s15, s10, 6
	s_lshl_b32 s15, s13, s15
	s_lshl_b32 s21, s14, 7
	s_add_i32 s15, s15, s21
	s_lshl_b32 s29, 8, s10
	v_lshlrev_b32_e32 v4, s10, v2
	v_lshl_add_u32 v4, v3, 4, v4
	s_lshl_b32 s21, s13, 8
	s_waitcnt lgkmcnt(0)
	s_add_u32 s4, s4, s71
	s_addc_u32 s5, s5, 0
	s_add_u32 s4, s4, s15
	s_addc_u32 s5, s5, 0
	s_add_u32 s6, s6, s72
	s_addc_u32 s7, s7, 0
	s_add_u32 s6, s6, s21
	s_addc_u32 s7, s7, 0
	s_add_u32 s8, s8, s72
	s_addc_u32 s9, s9, 0
	s_add_u32 s8, s8, s21
	s_addc_u32 s9, s9, 0
	global_load_dwordx4 v[100:103], v4, s[4:5] nt
	s_add_u32 s4, s4, s29
	s_addc_u32 s5, s5, 0
	global_load_dwordx4 v[104:107], v4, s[4:5] nt
	s_add_u32 s4, s4, s29
	s_addc_u32 s5, s5, 0
	global_load_dwordx4 v[108:111], v4, s[4:5] nt
	s_add_u32 s4, s4, s29
	s_addc_u32 s5, s5, 0
	global_load_dwordx4 v[112:115], v4, s[4:5] nt
	s_add_u32 s4, s4, s29
	s_addc_u32 s5, s5, 0
	global_load_dwordx4 v[116:119], v4, s[4:5] nt
	s_add_u32 s4, s4, s29
	s_addc_u32 s5, s5, 0
	global_load_dwordx4 v[120:123], v4, s[4:5] nt
	s_add_u32 s4, s4, s29
	s_addc_u32 s5, s5, 0
	global_load_dwordx4 v[124:127], v4, s[4:5] nt
	s_add_u32 s4, s4, s29
	s_addc_u32 s5, s5, 0
	global_load_dwordx4 v[128:131], v4, s[4:5] nt
	global_load_dword v206, v5, s[6:7]
	global_load_dword v207, v5, s[8:9]
	s_lshl_b32 s15, s14, 17
	s_lshl_b32 s21, s13, 7
	s_add_i32 s15, s15, s21
	s_add_u32 s36, s16, s69
	s_addc_u32 s37, s17, 0
	s_add_u32 s36, s36, s15
	s_addc_u32 s37, s37, 0
	s_lshl_b32 s15, s14, 7
	s_add_u32 s38, s16, s70
	s_addc_u32 s39, s17, 0
	s_add_u32 s38, s38, s15
	s_addc_u32 s39, s39, 0
	s_addk_i32 s30, 0x800
	s_cmp_lt_u32 s30, 0x4000
	s_cbranch_scc1 .Lgv2_w1
	s_cmp_lt_u32 s30, 0x5000
	s_cbranch_scc1 .Lgv2_pg
	s_cmp_lt_u32 s30, 0x5800
	s_cbranch_scc1 .Lgv2_wq
	s_cmp_lt_u32 s30, 0x5a00
	s_cbranch_scc1 .Lgv2_wk
	s_cmp_lt_u32 s30, 0x5c00
	s_cbranch_scc1 .Lgv2_wv
	s_mov_b32 s12, 0
	s_load_dwordx2 s[4:5], s[18:19], 0x98
	s_load_dwordx2 s[6:7], s[18:19], 0x100
	s_load_dwordx2 s[8:9], s[18:19], 0x108
	s_mov_b32 s10, 11
	s_mov_b32 s11, 4
	s_mov_b32 s69, 0x2d200000
	s_mov_b32 s70, 0x2e200000
	s_mov_b32 s47, 0x3000
	s_mov_b32 s71, 0
	s_mov_b32 s72, 0
	s_branch .Lgv2_common
.Lgv2_w1:
	s_lshr_b32 s15, s30, 13
	s_and_b32 s12, s30, 0x1fff
	s_load_dwordx2 s[4:5], s[18:19], 0xd0
	s_load_dwordx2 s[6:7], s[18:19], 0xc0
	s_load_dwordx2 s[8:9], s[18:19], 0xc8
	s_mov_b32 s10, 15
	s_mov_b32 s11, 8
	s_mov_b32 s73, 0x6f00000
	s_mov_b32 s69, 0x1200000
	s_mov_b32 s74, 0x19a000
	s_mov_b32 s70, 0x180000
	s_cmp_lg_u32 s15, 0
	s_cselect_b32 s69, s73, s69
	s_cselect_b32 s70, s74, s70
	s_mov_b32 s47, 0x8000
	s_lshl_b32 s71, s15, 26
	s_lshl_b32 s72, s15, 13
	s_branch .Lgv2_common
.Lgv2_pg:
	s_add_i32 s12, s30, 0xffffc000
	s_lshr_b32 s15, s12, 11
	s_and_b32 s12, s12, 0x7ff
	s_load_dwordx2 s[4:5], s[18:19], 0xf8
	s_load_dwordx2 s[6:7], s[18:19], 0xe0
	s_load_dwordx2 s[8:9], s[18:19], 0xe8
	s_mov_b32 s10, 13
	s_mov_b32 s11, 6
	s_mov_b32 s73, 0xb000000
	s_mov_b32 s69, 0x5300000
	s_mov_b32 s74, 0x1aa000
	s_mov_b32 s70, 0x190000
	s_cmp_lg_u32 s15, 0
	s_cselect_b32 s69, s73, s69
	s_cselect_b32 s70, s74, s70
	s_mov_b32 s47, 0x2000
	s_lshl_b32 s71, s15, 24
	s_lshl_b32 s72, s15, 13
	s_branch .Lgv2_common
.Lgv2_wq:
	s_add_i32 s12, s30, 0xffffb000
	s_load_dwordx2 s[4:5], s[18:19], 0xa8
	s_load_dwordx2 s[6:7], s[18:19], 0x100
	s_load_dwordx2 s[8:9], s[18:19], 0x108
	s_mov_b32 s10, 13
	s_mov_b32 s11, 6
	s_mov_b32 s69, 0x5f00000
	s_mov_b32 s70, 0x195000
	s_mov_b32 s47, 0x3000
	s_mov_b32 s71, 0
	s_mov_b32 s72, 0
	s_branch .Lgv2_common
.Lgv2_wk:
	s_add_i32 s12, s30, 0xffffa800
	s_load_dwordx2 s[4:5], s[18:19], 0x98
	s_load_dwordx2 s[6:7], s[18:19], 0x100
	s_load_dwordx2 s[8:9], s[18:19], 0x108
	s_mov_b32 s10, 11
	s_mov_b32 s11, 4
	s_mov_b32 s69, 0x5b00000
	s_mov_b32 s70, 0x194000
	s_mov_b32 s47, 0x3000
	s_mov_b32 s71, 0
	s_mov_b32 s72, 0
	s_branch .Lgv2_common
.Lgv2_wv:
	s_add_i32 s12, s30, 0xffffa600
	s_load_dwordx2 s[4:5], s[18:19], 0xa0
	s_load_dwordx2 s[6:7], s[18:19], 0x100
	s_load_dwordx2 s[8:9], s[18:19], 0x108
	s_mov_b32 s10, 11
	s_mov_b32 s11, 4
	s_mov_b32 s69, 0x5d00000
	s_mov_b32 s70, 0x194800
	s_mov_b32 s47, 0x3000
	s_mov_b32 s71, 0
	s_mov_b32 s72, 0
.Lgv2_common:
	s_lshr_b32 s13, s12, s11
	s_lshl_b32 s15, s13, s11
	s_sub_i32 s14, s12, s15
	s_add_i32 s15, s10, 6
	s_lshl_b32 s15, s13, s15
	s_lshl_b32 s21, s14, 7
	s_add_i32 s15, s15, s21
	s_lshl_b32 s29, 8, s10
	v_lshlrev_b32_e32 v4, s10, v2
	v_lshl_add_u32 v4, v3, 4, v4
	s_lshl_b32 s21, s13, 8
	s_waitcnt lgkmcnt(0)
	s_add_u32 s4, s4, s71
	s_addc_u32 s5, s5, 0
	s_add_u32 s4, s4, s15
	s_addc_u32 s5, s5, 0
	s_add_u32 s6, s6, s72
	s_addc_u32 s7, s7, 0
	s_add_u32 s6, s6, s21
	s_addc_u32 s7, s7, 0
	s_add_u32 s8, s8, s72
	s_addc_u32 s9, s9, 0
	s_add_u32 s8, s8, s21
	s_addc_u32 s9, s9, 0
	global_load_dwordx4 v[132:135], v4, s[4:5] nt
	s_add_u32 s4, s4, s29
	s_addc_u32 s5, s5, 0
	global_load_dwordx4 v[136:139], v4, s[4:5] nt
	s_add_u32 s4, s4, s29
	s_addc_u32 s5, s5, 0
	global_load_dwordx4 v[140:143], v4, s[4:5] nt
	s_add_u32 s4, s4, s29
	s_addc_u32 s5, s5, 0
	global_load_dwordx4 v[144:147], v4, s[4:5] nt
	s_add_u32 s4, s4, s29
	s_addc_u32 s5, s5, 0
	global_load_dwordx4 v[148:151], v4, s[4:5] nt
	s_add_u32 s4, s4, s29
	s_addc_u32 s5, s5, 0
	global_load_dwordx4 v[152:155], v4, s[4:5] nt
	s_add_u32 s4, s4, s29
	s_addc_u32 s5, s5, 0
	global_load_dwordx4 v[156:159], v4, s[4:5] nt
	s_add_u32 s4, s4, s29
	s_addc_u32 s5, s5, 0
	global_load_dwordx4 v[160:163], v4, s[4:5] nt
	global_load_dword v208, v5, s[6:7]
	global_load_dword v209, v5, s[8:9]
	s_lshl_b32 s15, s14, 17
	s_lshl_b32 s21, s13, 7
	s_add_i32 s15, s15, s21
	s_add_u32 s42, s16, s69
	s_addc_u32 s43, s17, 0
	s_add_u32 s42, s42, s15
	s_addc_u32 s43, s43, 0
	s_lshl_b32 s15, s14, 7
	s_add_u32 s44, s16, s70
	s_addc_u32 s45, s17, 0
	s_add_u32 s44, s44, s15
	s_addc_u32 s45, s45, 0
	s_addk_i32 s30, 0x800
	s_waitcnt vmcnt(10)
	ds_write_b32 v10, v206
	ds_write_b32 v10, v207 offset:256
	ds_read_b128 v[210:213], v11
	ds_read_b128 v[214:217], v11 offset:16
	ds_read_b128 v[218:221], v11 offset:256
	ds_read_b128 v[222:225], v11 offset:272
	s_waitcnt lgkmcnt(0)
	v_mul_f32_e32 v226, v100, v218
	v_mul_f32_e32 v100, v100, v210
	v_mul_f32_e32 v227, v101, v218
	v_mul_f32_e32 v101, v101, v210
	v_mul_f32_e32 v228, v102, v218
	v_mul_f32_e32 v102, v102, v210
	v_mul_f32_e32 v229, v103, v218
	v_mul_f32_e32 v103, v103, v210
	v_fmac_f32_e32 v226, v104, v219
	v_mul_f32_e32 v104, v104, v211
	v_fmac_f32_e32 v227, v105, v219
	v_mul_f32_e32 v105, v105, v211
	v_fmac_f32_e32 v228, v106, v219
	v_mul_f32_e32 v106, v106, v211
	v_fmac_f32_e32 v229, v107, v219
	v_mul_f32_e32 v107, v107, v211
	v_fmac_f32_e32 v226, v108, v220
	v_mul_f32_e32 v108, v108, v212
	v_fmac_f32_e32 v227, v109, v220
	v_mul_f32_e32 v109, v109, v212
	v_fmac_f32_e32 v228, v110, v220
	v_mul_f32_e32 v110, v110, v212
	v_fmac_f32_e32 v229, v111, v220
	v_mul_f32_e32 v111, v111, v212
	v_fmac_f32_e32 v226, v112, v221
	v_mul_f32_e32 v112, v112, v213
	v_fmac_f32_e32 v227, v113, v221
	v_mul_f32_e32 v113, v113, v213
	v_fmac_f32_e32 v228, v114, v221
	v_mul_f32_e32 v114, v114, v213
	v_fmac_f32_e32 v229, v115, v221
	v_mul_f32_e32 v115, v115, v213
	v_fmac_f32_e32 v226, v116, v222
	v_mul_f32_e32 v116, v116, v214
	v_fmac_f32_e32 v227, v117, v222
	v_mul_f32_e32 v117, v117, v214
	v_fmac_f32_e32 v228, v118, v222
	v_mul_f32_e32 v118, v118, v214
	v_fmac_f32_e32 v229, v119, v222
	v_mul_f32_e32 v119, v119, v214
	v_fmac_f32_e32 v226, v120, v223
	v_mul_f32_e32 v120, v120, v215
	v_fmac_f32_e32 v227, v121, v223
	v_mul_f32_e32 v121, v121, v215
	v_fmac_f32_e32 v228, v122, v223
	v_mul_f32_e32 v122, v122, v215
	v_fmac_f32_e32 v229, v123, v223
	v_mul_f32_e32 v123, v123, v215
	v_fmac_f32_e32 v226, v124, v224
	v_mul_f32_e32 v124, v124, v216
	v_fmac_f32_e32 v227, v125, v224
	v_mul_f32_e32 v125, v125, v216
	v_fmac_f32_e32 v228, v126, v224
	v_mul_f32_e32 v126, v126, v216
	v_fmac_f32_e32 v229, v127, v224
	v_mul_f32_e32 v127, v127, v216
	v_fmac_f32_e32 v226, v128, v225
	v_mul_f32_e32 v128, v128, v217
	v_fmac_f32_e32 v227, v129, v225
	v_mul_f32_e32 v129, v129, v217
	v_fmac_f32_e32 v228, v130, v225
	v_mul_f32_e32 v130, v130, v217
	v_fmac_f32_e32 v229, v131, v225
	v_mul_f32_e32 v131, v131, v217
	ds_write_b128 v21, v[100:103]
	ds_write_b128 v22, v[104:107] offset:1024
	ds_write_b128 v23, v[108:111] offset:2048
	ds_write_b128 v24, v[112:115] offset:3072
	ds_write_b128 v25, v[116:119] offset:4096
	ds_write_b128 v26, v[120:123] offset:5120
	ds_write_b128 v27, v[124:127] offset:6144
	ds_write_b128 v28, v[128:131] offset:7168
	ds_read2_b32 v[100:101], v29 offset1:32
	ds_read2_b32 v[102:103], v29 offset0:64 offset1:96
	ds_read2_b32 v[104:105], v29 offset0:128 offset1:160
	ds_read2_b32 v[106:107], v29 offset0:192 offset1:224
	ds_read2_b32 v[108:109], v30 offset1:32
	ds_read2_b32 v[110:111], v30 offset0:64 offset1:96
	ds_read2_b32 v[112:113], v30 offset0:128 offset1:160
	ds_read2_b32 v[114:115], v30 offset0:192 offset1:224
	ds_read2_b32 v[116:117], v31 offset1:32
	ds_read2_b32 v[118:119], v31 offset0:64 offset1:96
	ds_read2_b32 v[120:121], v31 offset0:128 offset1:160
	ds_read2_b32 v[122:123], v31 offset0:192 offset1:224
	ds_read2_b32 v[124:125], v32 offset1:32
	ds_read2_b32 v[126:127], v32 offset0:64 offset1:96
	ds_read2_b32 v[128:129], v32 offset0:128 offset1:160
	ds_read2_b32 v[130:131], v32 offset0:192 offset1:224
	ds_bpermute_b32 v234, v12, v226
	ds_bpermute_b32 v235, v12, v227
	ds_bpermute_b32 v236, v12, v228
	ds_bpermute_b32 v237, v12, v229
	s_waitcnt lgkmcnt(4)
	v_cvt_pk_bf16_f32 v164, v100, v101
	v_cvt_pk_bf16_f32 v165, v102, v103
	v_cvt_pk_bf16_f32 v166, v104, v105
	v_cvt_pk_bf16_f32 v167, v106, v107
	v_cvt_pk_bf16_f32 v168, v108, v109
	v_cvt_pk_bf16_f32 v169, v110, v111
	v_cvt_pk_bf16_f32 v170, v112, v113
	v_cvt_pk_bf16_f32 v171, v114, v115
	v_cvt_pk_bf16_f32 v172, v116, v117
	v_cvt_pk_bf16_f32 v173, v118, v119
	v_cvt_pk_bf16_f32 v174, v120, v121
	v_cvt_pk_bf16_f32 v175, v122, v123
	v_cvt_pk_bf16_f32 v176, v124, v125
	v_cvt_pk_bf16_f32 v177, v126, v127
	v_cvt_pk_bf16_f32 v178, v128, v129
	v_cvt_pk_bf16_f32 v179, v130, v131
	s_waitcnt lgkmcnt(0)
	v_add_f32_e32 v226, v226, v234
	v_add_f32_e32 v227, v227, v235
	v_add_f32_e32 v228, v228, v236
	v_add_f32_e32 v229, v229, v237
	ds_bpermute_b32 v234, v13, v226
	ds_bpermute_b32 v235, v13, v227
	ds_bpermute_b32 v236, v13, v228
	ds_bpermute_b32 v237, v13, v229
	v_lshlrev_b32_e32 v238, 16, v164
	v_and_b32_e32 v239, s59, v164
	v_add_f32_e32 v230, v238, v239
	v_lshlrev_b32_e32 v238, 16, v165
	v_and_b32_e32 v239, s59, v165
	v_add_f32_e32 v230, v230, v238
	v_add_f32_e32 v230, v230, v239
	v_lshlrev_b32_e32 v238, 16, v166
	v_and_b32_e32 v239, s59, v166
	v_add_f32_e32 v230, v230, v238
	v_add_f32_e32 v230, v230, v239
	v_lshlrev_b32_e32 v238, 16, v167
	v_and_b32_e32 v239, s59, v167
	v_add_f32_e32 v230, v230, v238
	v_add_f32_e32 v230, v230, v239
	v_lshlrev_b32_e32 v238, 16, v168
	v_and_b32_e32 v239, s59, v168
	v_add_f32_e32 v231, v238, v239
	v_lshlrev_b32_e32 v238, 16, v169
	v_and_b32_e32 v239, s59, v169
	v_add_f32_e32 v231, v231, v238
	v_add_f32_e32 v231, v231, v239
	v_lshlrev_b32_e32 v238, 16, v170
	v_and_b32_e32 v239, s59, v170
	v_add_f32_e32 v231, v231, v238
	v_add_f32_e32 v231, v231, v239
	v_lshlrev_b32_e32 v238, 16, v171
	v_and_b32_e32 v239, s59, v171
	v_add_f32_e32 v231, v231, v238
	v_add_f32_e32 v231, v231, v239
	s_waitcnt lgkmcnt(0)
	v_add_f32_e32 v226, v226, v234
	v_add_f32_e32 v227, v227, v235
	v_add_f32_e32 v228, v228, v236
	v_add_f32_e32 v229, v229, v237
	ds_bpermute_b32 v234, v14, v226
	ds_bpermute_b32 v235, v14, v227
	ds_bpermute_b32 v236, v14, v228
	ds_bpermute_b32 v237, v14, v229
	v_lshlrev_b32_e32 v238, 16, v172
	v_and_b32_e32 v239, s59, v172
	v_add_f32_e32 v232, v238, v239
	v_lshlrev_b32_e32 v238, 16, v173
	v_and_b32_e32 v239, s59, v173
	v_add_f32_e32 v232, v232, v238
	v_add_f32_e32 v232, v232, v239
	v_lshlrev_b32_e32 v238, 16, v174
	v_and_b32_e32 v239, s59, v174
	v_add_f32_e32 v232, v232, v238
	v_add_f32_e32 v232, v232, v239
	v_lshlrev_b32_e32 v238, 16, v175
	v_and_b32_e32 v239, s59, v175
	v_add_f32_e32 v232, v232, v238
	v_add_f32_e32 v232, v232, v239
	v_lshlrev_b32_e32 v238, 16, v176
	v_and_b32_e32 v239, s59, v176
	v_add_f32_e32 v233, v238, v239
	v_lshlrev_b32_e32 v238, 16, v177
	v_and_b32_e32 v239, s59, v177
	v_add_f32_e32 v233, v233, v238
	v_add_f32_e32 v233, v233, v239
	v_lshlrev_b32_e32 v238, 16, v178
	v_and_b32_e32 v239, s59, v178
	v_add_f32_e32 v233, v233, v238
	v_add_f32_e32 v233, v233, v239
	v_lshlrev_b32_e32 v238, 16, v179
	v_and_b32_e32 v239, s59, v179
	v_add_f32_e32 v233, v233, v238
	v_add_f32_e32 v233, v233, v239
	s_nop 1
	v_add_f32_dpp v230, v230, v230 quad_perm:[1,0,3,2] row_mask:0xf bank_mask:0xf
	v_add_f32_dpp v231, v231, v231 quad_perm:[1,0,3,2] row_mask:0xf bank_mask:0xf
	v_add_f32_dpp v232, v232, v232 quad_perm:[1,0,3,2] row_mask:0xf bank_mask:0xf
	v_add_f32_dpp v233, v233, v233 quad_perm:[1,0,3,2] row_mask:0xf bank_mask:0xf
	v_add_f32_dpp v230, v230, v230 quad_perm:[2,3,0,1] row_mask:0xf bank_mask:0xf
	v_add_f32_dpp v231, v231, v231 quad_perm:[2,3,0,1] row_mask:0xf bank_mask:0xf
	v_add_f32_dpp v232, v232, v232 quad_perm:[2,3,0,1] row_mask:0xf bank_mask:0xf
	v_add_f32_dpp v233, v233, v233 quad_perm:[2,3,0,1] row_mask:0xf bank_mask:0xf
	v_add_f32_dpp v230, v230, v230 row_half_mirror row_mask:0xf bank_mask:0xf
	v_add_f32_dpp v231, v231, v231 row_half_mirror row_mask:0xf bank_mask:0xf
	v_add_f32_dpp v232, v232, v232 row_half_mirror row_mask:0xf bank_mask:0xf
	v_add_f32_dpp v233, v233, v233 row_half_mirror row_mask:0xf bank_mask:0xf
	s_waitcnt lgkmcnt(0)
	v_add_f32_e32 v226, v226, v234
	v_add_f32_e32 v227, v227, v235
	v_add_f32_e32 v228, v228, v236
	v_add_f32_e32 v229, v229, v237
	global_store_dwordx4 v17, v[164:167], s[36:37]
	global_store_dwordx4 v18, v[168:171], s[36:37]
	global_store_dwordx4 v19, v[172:175], s[36:37]
	global_store_dwordx4 v20, v[176:179], s[36:37]
	s_add_u32 s48, s38, s40
	s_addc_u32 s49, s39, 0
	s_mov_b64 exec, s[56:57]
	global_atomic_add_f32 v15, v230, s[38:39]
	global_atomic_add_f32 v15, v231, s[38:39] offset:32
	global_atomic_add_f32 v15, v232, s[38:39] offset:64
	global_atomic_add_f32 v15, v233, s[38:39] offset:96
	s_mov_b64 exec, s[64:65]
	global_atomic_add_f32 v16, v226, s[48:49]
	global_atomic_add_f32 v16, v227, s[48:49] offset:4
	global_atomic_add_f32 v16, v228, s[48:49] offset:8
	global_atomic_add_f32 v16, v229, s[48:49] offset:12
	s_mov_b64 exec, -1
	s_cmp_lt_u32 s30, 0x4000
	s_cbranch_scc1 .Lgv3_w1
	s_cmp_lt_u32 s30, 0x5000
	s_cbranch_scc1 .Lgv3_pg
	s_cmp_lt_u32 s30, 0x5800
	s_cbranch_scc1 .Lgv3_wq
	s_cmp_lt_u32 s30, 0x5a00
	s_cbranch_scc1 .Lgv3_wk
	s_cmp_lt_u32 s30, 0x5c00
	s_cbranch_scc1 .Lgv3_wv
	s_mov_b32 s12, 0
	s_load_dwordx2 s[4:5], s[18:19], 0x98
	s_load_dwordx2 s[6:7], s[18:19], 0x100
	s_load_dwordx2 s[8:9], s[18:19], 0x108
	s_mov_b32 s10, 11
	s_mov_b32 s11, 4
	s_mov_b32 s69, 0x2d200000
	s_mov_b32 s70, 0x2e200000
	s_mov_b32 s40, 0x3000
	s_mov_b32 s71, 0
	s_mov_b32 s72, 0
	s_branch .Lgv3_common

.Lgv3_common:
	s_lshr_b32 s13, s12, s11
	s_lshl_b32 s15, s13, s11
	s_sub_i32 s14, s12, s15
	s_add_i32 s15, s10, 6
	s_lshl_b32 s15, s13, s15
	s_lshl_b32 s21, s14, 7
	s_add_i32 s15, s15, s21
	s_lshl_b32 s29, 8, s10
	v_lshlrev_b32_e32 v4, s10, v2
	v_lshl_add_u32 v4, v3, 4, v4
	s_lshl_b32 s21, s13, 8
	s_waitcnt lgkmcnt(0)
	s_add_u32 s4, s4, s71
	s_addc_u32 s5, s5, 0
	s_add_u32 s4, s4, s15
	s_addc_u32 s5, s5, 0
	s_add_u32 s6, s6, s72
	s_addc_u32 s7, s7, 0
	s_add_u32 s6, s6, s21
	s_addc_u32 s7, s7, 0
	s_add_u32 s8, s8, s72
	s_addc_u32 s9, s9, 0
	s_add_u32 s8, s8, s21
	s_addc_u32 s9, s9, 0
	global_load_dwordx4 v[100:103], v4, s[4:5] nt
	s_add_u32 s4, s4, s29
	s_addc_u32 s5, s5, 0
	global_load_dwordx4 v[104:107], v4, s[4:5] nt
	s_add_u32 s4, s4, s29
	s_addc_u32 s5, s5, 0
	global_load_dwordx4 v[108:111], v4, s[4:5] nt
	s_add_u32 s4, s4, s29
	s_addc_u32 s5, s5, 0
	global_load_dwordx4 v[112:115], v4, s[4:5] nt
	s_add_u32 s4, s4, s29
	s_addc_u32 s5, s5, 0
	global_load_dwordx4 v[116:119], v4, s[4:5] nt
	s_add_u32 s4, s4, s29
	s_addc_u32 s5, s5, 0
	global_load_dwordx4 v[120:123], v4, s[4:5] nt
	s_add_u32 s4, s4, s29
	s_addc_u32 s5, s5, 0
	global_load_dwordx4 v[124:127], v4, s[4:5] nt
	s_add_u32 s4, s4, s29
	s_addc_u32 s5, s5, 0
	global_load_dwordx4 v[128:131], v4, s[4:5] nt
	global_load_dword v206, v5, s[6:7]
	global_load_dword v207, v5, s[8:9]
	s_lshl_b32 s15, s14, 17
	s_lshl_b32 s21, s13, 7
	s_add_i32 s15, s15, s21
	s_add_u32 s36, s16, s69
	s_addc_u32 s37, s17, 0
	s_add_u32 s36, s36, s15
	s_addc_u32 s37, s37, 0
	s_lshl_b32 s15, s14, 7
	s_add_u32 s38, s16, s70
	s_addc_u32 s39, s17, 0
	s_add_u32 s38, s38, s15
	s_addc_u32 s39, s39, 0
	s_addk_i32 s30, 0x800
	s_mov_b32 s3, 5
.Lgv_loop:
	s_waitcnt vmcnt(22)
	ds_write_b32 v10, v208
	ds_write_b32 v10, v209 offset:256
	ds_read_b128 v[210:213], v11
	ds_read_b128 v[214:217], v11 offset:16
	ds_read_b128 v[218:221], v11 offset:256
	ds_read_b128 v[222:225], v11 offset:272
	s_waitcnt lgkmcnt(0)
	v_mul_f32_e32 v226, v132, v218
	v_mul_f32_e32 v132, v132, v210
	v_mul_f32_e32 v227, v133, v218
	v_mul_f32_e32 v133, v133, v210
	v_mul_f32_e32 v228, v134, v218
	v_mul_f32_e32 v134, v134, v210
	v_mul_f32_e32 v229, v135, v218
	v_mul_f32_e32 v135, v135, v210
	v_fmac_f32_e32 v226, v136, v219
	v_mul_f32_e32 v136, v136, v211
	v_fmac_f32_e32 v227, v137, v219
	v_mul_f32_e32 v137, v137, v211
	v_fmac_f32_e32 v228, v138, v219
	v_mul_f32_e32 v138, v138, v211
	v_fmac_f32_e32 v229, v139, v219
	v_mul_f32_e32 v139, v139, v211
	v_fmac_f32_e32 v226, v140, v220
	v_mul_f32_e32 v140, v140, v212
	v_fmac_f32_e32 v227, v141, v220
	v_mul_f32_e32 v141, v141, v212
	v_fmac_f32_e32 v228, v142, v220
	v_mul_f32_e32 v142, v142, v212
	v_fmac_f32_e32 v229, v143, v220
	v_mul_f32_e32 v143, v143, v212
	v_fmac_f32_e32 v226, v144, v221
	v_mul_f32_e32 v144, v144, v213
	v_fmac_f32_e32 v227, v145, v221
	v_mul_f32_e32 v145, v145, v213
	v_fmac_f32_e32 v228, v146, v221
	v_mul_f32_e32 v146, v146, v213
	v_fmac_f32_e32 v229, v147, v221
	v_mul_f32_e32 v147, v147, v213
	v_fmac_f32_e32 v226, v148, v222
	v_mul_f32_e32 v148, v148, v214
	v_fmac_f32_e32 v227, v149, v222
	v_mul_f32_e32 v149, v149, v214
	v_fmac_f32_e32 v228, v150, v222
	v_mul_f32_e32 v150, v150, v214
	v_fmac_f32_e32 v229, v151, v222
	v_mul_f32_e32 v151, v151, v214
	v_fmac_f32_e32 v226, v152, v223
	v_mul_f32_e32 v152, v152, v215
	v_fmac_f32_e32 v227, v153, v223
	v_mul_f32_e32 v153, v153, v215
	v_fmac_f32_e32 v228, v154, v223
	v_mul_f32_e32 v154, v154, v215
	v_fmac_f32_e32 v229, v155, v223
	v_mul_f32_e32 v155, v155, v215
	v_fmac_f32_e32 v226, v156, v224
	v_mul_f32_e32 v156, v156, v216
	v_fmac_f32_e32 v227, v157, v224
	v_mul_f32_e32 v157, v157, v216
	v_fmac_f32_e32 v228, v158, v224
	v_mul_f32_e32 v158, v158, v216
	v_fmac_f32_e32 v229, v159, v224
	v_mul_f32_e32 v159, v159, v216
	v_fmac_f32_e32 v226, v160, v225
	v_mul_f32_e32 v160, v160, v217
	v_fmac_f32_e32 v227, v161, v225
	v_mul_f32_e32 v161, v161, v217
	v_fmac_f32_e32 v228, v162, v225
	v_mul_f32_e32 v162, v162, v217
	v_fmac_f32_e32 v229, v163, v225
	v_mul_f32_e32 v163, v163, v217
	ds_write_b128 v21, v[132:135]
	ds_write_b128 v22, v[136:139] offset:1024
	ds_write_b128 v23, v[140:143] offset:2048
	ds_write_b128 v24, v[144:147] offset:3072
	ds_write_b128 v25, v[148:151] offset:4096
	ds_write_b128 v26, v[152:155] offset:5120
	ds_write_b128 v27, v[156:159] offset:6144
	ds_write_b128 v28, v[160:163] offset:7168
	ds_read2_b32 v[132:133], v29 offset1:32
	ds_read2_b32 v[134:135], v29 offset0:64 offset1:96
	ds_read2_b32 v[136:137], v29 offset0:128 offset1:160
	ds_read2_b32 v[138:139], v29 offset0:192 offset1:224
	ds_read2_b32 v[140:141], v30 offset1:32
	ds_read2_b32 v[142:143], v30 offset0:64 offset1:96
	ds_read2_b32 v[144:145], v30 offset0:128 offset1:160
	ds_read2_b32 v[146:147], v30 offset0:192 offset1:224
	ds_read2_b32 v[148:149], v31 offset1:32
	ds_read2_b32 v[150:151], v31 offset0:64 offset1:96
	ds_read2_b32 v[152:153], v31 offset0:128 offset1:160
	ds_read2_b32 v[154:155], v31 offset0:192 offset1:224
	ds_read2_b32 v[156:157], v32 offset1:32
	ds_read2_b32 v[158:159], v32 offset0:64 offset1:96
	ds_read2_b32 v[160:161], v32 offset0:128 offset1:160
	ds_read2_b32 v[162:163], v32 offset0:192 offset1:224
	ds_bpermute_b32 v234, v12, v226
	ds_bpermute_b32 v235, v12, v227
	ds_bpermute_b32 v236, v12, v228
	ds_bpermute_b32 v237, v12, v229
	s_waitcnt lgkmcnt(4)
	v_cvt_pk_bf16_f32 v190, v132, v133
	v_cvt_pk_bf16_f32 v191, v134, v135
	v_cvt_pk_bf16_f32 v192, v136, v137
	v_cvt_pk_bf16_f32 v193, v138, v139
	v_cvt_pk_bf16_f32 v194, v140, v141
	v_cvt_pk_bf16_f32 v195, v142, v143
	v_cvt_pk_bf16_f32 v196, v144, v145
	v_cvt_pk_bf16_f32 v197, v146, v147
	v_cvt_pk_bf16_f32 v198, v148, v149
	v_cvt_pk_bf16_f32 v199, v150, v151
	v_cvt_pk_bf16_f32 v200, v152, v153
	v_cvt_pk_bf16_f32 v201, v154, v155
	v_cvt_pk_bf16_f32 v202, v156, v157
	v_cvt_pk_bf16_f32 v203, v158, v159
	v_cvt_pk_bf16_f32 v204, v160, v161
	v_cvt_pk_bf16_f32 v205, v162, v163
	s_waitcnt lgkmcnt(0)
	v_add_f32_e32 v226, v226, v234
	v_add_f32_e32 v227, v227, v235
	v_add_f32_e32 v228, v228, v236
	v_add_f32_e32 v229, v229, v237
	ds_bpermute_b32 v234, v13, v226
	ds_bpermute_b32 v235, v13, v227
	ds_bpermute_b32 v236, v13, v228
	ds_bpermute_b32 v237, v13, v229
	v_lshlrev_b32_e32 v238, 16, v190
	v_and_b32_e32 v239, s59, v190
	v_add_f32_e32 v230, v238, v239
	v_lshlrev_b32_e32 v238, 16, v191
	v_and_b32_e32 v239, s59, v191
	v_add_f32_e32 v230, v230, v238
	v_add_f32_e32 v230, v230, v239
	v_lshlrev_b32_e32 v238, 16, v192
	v_and_b32_e32 v239, s59, v192
	v_add_f32_e32 v230, v230, v238
	v_add_f32_e32 v230, v230, v239
	v_lshlrev_b32_e32 v238, 16, v193
	v_and_b32_e32 v239, s59, v193
	v_add_f32_e32 v230, v230, v238
	v_add_f32_e32 v230, v230, v239
	v_lshlrev_b32_e32 v238, 16, v194
	v_and_b32_e32 v239, s59, v194
	v_add_f32_e32 v231, v238, v239
	v_lshlrev_b32_e32 v238, 16, v195
	v_and_b32_e32 v239, s59, v195
	v_add_f32_e32 v231, v231, v238
	v_add_f32_e32 v231, v231, v239
	v_lshlrev_b32_e32 v238, 16, v196
	v_and_b32_e32 v239, s59, v196
	v_add_f32_e32 v231, v231, v238
	v_add_f32_e32 v231, v231, v239
	v_lshlrev_b32_e32 v238, 16, v197
	v_and_b32_e32 v239, s59, v197
	v_add_f32_e32 v231, v231, v238
	v_add_f32_e32 v231, v231, v239
	s_waitcnt lgkmcnt(0)
	v_add_f32_e32 v226, v226, v234
	v_add_f32_e32 v227, v227, v235
	v_add_f32_e32 v228, v228, v236
	v_add_f32_e32 v229, v229, v237
	ds_bpermute_b32 v234, v14, v226
	ds_bpermute_b32 v235, v14, v227
	ds_bpermute_b32 v236, v14, v228
	ds_bpermute_b32 v237, v14, v229
	v_lshlrev_b32_e32 v238, 16, v198
	v_and_b32_e32 v239, s59, v198
	v_add_f32_e32 v232, v238, v239
	v_lshlrev_b32_e32 v238, 16, v199
	v_and_b32_e32 v239, s59, v199
	v_add_f32_e32 v232, v232, v238
	v_add_f32_e32 v232, v232, v239
	v_lshlrev_b32_e32 v238, 16, v200
	v_and_b32_e32 v239, s59, v200
	v_add_f32_e32 v232, v232, v238
	v_add_f32_e32 v232, v232, v239
	v_lshlrev_b32_e32 v238, 16, v201
	v_and_b32_e32 v239, s59, v201
	v_add_f32_e32 v232, v232, v238
	v_add_f32_e32 v232, v232, v239
	v_lshlrev_b32_e32 v238, 16, v202
	v_and_b32_e32 v239, s59, v202
	v_add_f32_e32 v233, v238, v239
	v_lshlrev_b32_e32 v238, 16, v203
	v_and_b32_e32 v239, s59, v203
	v_add_f32_e32 v233, v233, v238
	v_add_f32_e32 v233, v233, v239
	v_lshlrev_b32_e32 v238, 16, v204
	v_and_b32_e32 v239, s59, v204
	v_add_f32_e32 v233, v233, v238
	v_add_f32_e32 v233, v233, v239
	v_lshlrev_b32_e32 v238, 16, v205
	v_and_b32_e32 v239, s59, v205
	v_add_f32_e32 v233, v233, v238
	v_add_f32_e32 v233, v233, v239
	s_nop 1
	v_add_f32_dpp v230, v230, v230 quad_perm:[1,0,3,2] row_mask:0xf bank_mask:0xf
	v_add_f32_dpp v231, v231, v231 quad_perm:[1,0,3,2] row_mask:0xf bank_mask:0xf
	v_add_f32_dpp v232, v232, v232 quad_perm:[1,0,3,2] row_mask:0xf bank_mask:0xf
	v_add_f32_dpp v233, v233, v233 quad_perm:[1,0,3,2] row_mask:0xf bank_mask:0xf
	v_add_f32_dpp v230, v230, v230 quad_perm:[2,3,0,1] row_mask:0xf bank_mask:0xf
	v_add_f32_dpp v231, v231, v231 quad_perm:[2,3,0,1] row_mask:0xf bank_mask:0xf
	v_add_f32_dpp v232, v232, v232 quad_perm:[2,3,0,1] row_mask:0xf bank_mask:0xf
	v_add_f32_dpp v233, v233, v233 quad_perm:[2,3,0,1] row_mask:0xf bank_mask:0xf
	v_add_f32_dpp v230, v230, v230 row_half_mirror row_mask:0xf bank_mask:0xf
	v_add_f32_dpp v231, v231, v231 row_half_mirror row_mask:0xf bank_mask:0xf
	v_add_f32_dpp v232, v232, v232 row_half_mirror row_mask:0xf bank_mask:0xf
	v_add_f32_dpp v233, v233, v233 row_half_mirror row_mask:0xf bank_mask:0xf
	s_waitcnt lgkmcnt(0)
	v_add_f32_e32 v226, v226, v234
	v_add_f32_e32 v227, v227, v235
	v_add_f32_e32 v228, v228, v236
	v_add_f32_e32 v229, v229, v237
	global_store_dwordx4 v17, v[190:193], s[42:43]
	global_store_dwordx4 v18, v[194:197], s[42:43]
	global_store_dwordx4 v19, v[198:201], s[42:43]
	global_store_dwordx4 v20, v[202:205], s[42:43]
	s_add_u32 s48, s44, s47
	s_addc_u32 s49, s45, 0
	s_mov_b64 exec, s[56:57]
	global_atomic_add_f32 v15, v230, s[44:45]
	global_atomic_add_f32 v15, v231, s[44:45] offset:32
	global_atomic_add_f32 v15, v232, s[44:45] offset:64
	global_atomic_add_f32 v15, v233, s[44:45] offset:96
	s_mov_b64 exec, s[64:65]
	global_atomic_add_f32 v16, v226, s[48:49]
	global_atomic_add_f32 v16, v227, s[48:49] offset:4
	global_atomic_add_f32 v16, v228, s[48:49] offset:8
	global_atomic_add_f32 v16, v229, s[48:49] offset:12
	s_mov_b64 exec, -1
	s_cmp_lt_u32 s30, 0x4000
	s_cbranch_scc1 .Lgv4_w1
	s_cmp_lt_u32 s30, 0x5000
	s_cbranch_scc1 .Lgv4_pg
	s_cmp_lt_u32 s30, 0x5800
	s_cbranch_scc1 .Lgv4_wq
	s_cmp_lt_u32 s30, 0x5a00
	s_cbranch_scc1 .Lgv4_wk
	s_cmp_lt_u32 s30, 0x5c00
	s_cbranch_scc1 .Lgv4_wv
	s_mov_b32 s12, 0
	s_load_dwordx2 s[4:5], s[18:19], 0x98
	s_load_dwordx2 s[6:7], s[18:19], 0x100
	s_load_dwordx2 s[8:9], s[18:19], 0x108
	s_mov_b32 s10, 11
	s_mov_b32 s11, 4
	s_mov_b32 s69, 0x2d200000
	s_mov_b32 s70, 0x2e200000
	s_mov_b32 s47, 0x3000
	s_mov_b32 s71, 0
	s_mov_b32 s72, 0
	s_branch .Lgv4_common

.Lgv4_common:
	s_lshr_b32 s13, s12, s11
	s_lshl_b32 s15, s13, s11
	s_sub_i32 s14, s12, s15
	s_add_i32 s15, s10, 6
	s_lshl_b32 s15, s13, s15
	s_lshl_b32 s21, s14, 7
	s_add_i32 s15, s15, s21
	s_lshl_b32 s29, 8, s10
	v_lshlrev_b32_e32 v4, s10, v2
	v_lshl_add_u32 v4, v3, 4, v4
	s_lshl_b32 s21, s13, 8
	s_waitcnt lgkmcnt(0)
	s_add_u32 s4, s4, s71
	s_addc_u32 s5, s5, 0
	s_add_u32 s4, s4, s15
	s_addc_u32 s5, s5, 0
	s_add_u32 s6, s6, s72
	s_addc_u32 s7, s7, 0
	s_add_u32 s6, s6, s21
	s_addc_u32 s7, s7, 0
	s_add_u32 s8, s8, s72
	s_addc_u32 s9, s9, 0
	s_add_u32 s8, s8, s21
	s_addc_u32 s9, s9, 0
	global_load_dwordx4 v[132:135], v4, s[4:5] nt
	s_add_u32 s4, s4, s29
	s_addc_u32 s5, s5, 0
	global_load_dwordx4 v[136:139], v4, s[4:5] nt
	s_add_u32 s4, s4, s29
	s_addc_u32 s5, s5, 0
	global_load_dwordx4 v[140:143], v4, s[4:5] nt
	s_add_u32 s4, s4, s29
	s_addc_u32 s5, s5, 0
	global_load_dwordx4 v[144:147], v4, s[4:5] nt
	s_add_u32 s4, s4, s29
	s_addc_u32 s5, s5, 0
	global_load_dwordx4 v[148:151], v4, s[4:5] nt
	s_add_u32 s4, s4, s29
	s_addc_u32 s5, s5, 0
	global_load_dwordx4 v[152:155], v4, s[4:5] nt
	s_add_u32 s4, s4, s29
	s_addc_u32 s5, s5, 0
	global_load_dwordx4 v[156:159], v4, s[4:5] nt
	s_add_u32 s4, s4, s29
	s_addc_u32 s5, s5, 0
	global_load_dwordx4 v[160:163], v4, s[4:5] nt
	global_load_dword v208, v5, s[6:7]
	global_load_dword v209, v5, s[8:9]
	s_lshl_b32 s15, s14, 17
	s_lshl_b32 s21, s13, 7
	s_add_i32 s15, s15, s21
	s_add_u32 s42, s16, s69
	s_addc_u32 s43, s17, 0
	s_add_u32 s42, s42, s15
	s_addc_u32 s43, s43, 0
	s_lshl_b32 s15, s14, 7
	s_add_u32 s44, s16, s70
	s_addc_u32 s45, s17, 0
	s_add_u32 s44, s44, s15
	s_addc_u32 s45, s45, 0
	s_addk_i32 s30, 0x800
	s_waitcnt vmcnt(22)
	ds_write_b32 v10, v206
	ds_write_b32 v10, v207 offset:256
	ds_read_b128 v[210:213], v11
	ds_read_b128 v[214:217], v11 offset:16
	ds_read_b128 v[218:221], v11 offset:256
	ds_read_b128 v[222:225], v11 offset:272
	s_waitcnt lgkmcnt(0)
	v_mul_f32_e32 v226, v100, v218
	v_mul_f32_e32 v100, v100, v210
	v_mul_f32_e32 v227, v101, v218
	v_mul_f32_e32 v101, v101, v210
	v_mul_f32_e32 v228, v102, v218
	v_mul_f32_e32 v102, v102, v210
	v_mul_f32_e32 v229, v103, v218
	v_mul_f32_e32 v103, v103, v210
	v_fmac_f32_e32 v226, v104, v219
	v_mul_f32_e32 v104, v104, v211
	v_fmac_f32_e32 v227, v105, v219
	v_mul_f32_e32 v105, v105, v211
	v_fmac_f32_e32 v228, v106, v219
	v_mul_f32_e32 v106, v106, v211
	v_fmac_f32_e32 v229, v107, v219
	v_mul_f32_e32 v107, v107, v211
	v_fmac_f32_e32 v226, v108, v220
	v_mul_f32_e32 v108, v108, v212
	v_fmac_f32_e32 v227, v109, v220
	v_mul_f32_e32 v109, v109, v212
	v_fmac_f32_e32 v228, v110, v220
	v_mul_f32_e32 v110, v110, v212
	v_fmac_f32_e32 v229, v111, v220
	v_mul_f32_e32 v111, v111, v212
	v_fmac_f32_e32 v226, v112, v221
	v_mul_f32_e32 v112, v112, v213
	v_fmac_f32_e32 v227, v113, v221
	v_mul_f32_e32 v113, v113, v213
	v_fmac_f32_e32 v228, v114, v221
	v_mul_f32_e32 v114, v114, v213
	v_fmac_f32_e32 v229, v115, v221
	v_mul_f32_e32 v115, v115, v213
	v_fmac_f32_e32 v226, v116, v222
	v_mul_f32_e32 v116, v116, v214
	v_fmac_f32_e32 v227, v117, v222
	v_mul_f32_e32 v117, v117, v214
	v_fmac_f32_e32 v228, v118, v222
	v_mul_f32_e32 v118, v118, v214
	v_fmac_f32_e32 v229, v119, v222
	v_mul_f32_e32 v119, v119, v214
	v_fmac_f32_e32 v226, v120, v223
	v_mul_f32_e32 v120, v120, v215
	v_fmac_f32_e32 v227, v121, v223
	v_mul_f32_e32 v121, v121, v215
	v_fmac_f32_e32 v228, v122, v223
	v_mul_f32_e32 v122, v122, v215
	v_fmac_f32_e32 v229, v123, v223
	v_mul_f32_e32 v123, v123, v215
	v_fmac_f32_e32 v226, v124, v224
	v_mul_f32_e32 v124, v124, v216
	v_fmac_f32_e32 v227, v125, v224
	v_mul_f32_e32 v125, v125, v216
	v_fmac_f32_e32 v228, v126, v224
	v_mul_f32_e32 v126, v126, v216
	v_fmac_f32_e32 v229, v127, v224
	v_mul_f32_e32 v127, v127, v216
	v_fmac_f32_e32 v226, v128, v225
	v_mul_f32_e32 v128, v128, v217
	v_fmac_f32_e32 v227, v129, v225
	v_mul_f32_e32 v129, v129, v217
	v_fmac_f32_e32 v228, v130, v225
	v_mul_f32_e32 v130, v130, v217
	v_fmac_f32_e32 v229, v131, v225
	v_mul_f32_e32 v131, v131, v217
	ds_write_b128 v21, v[100:103]
	ds_write_b128 v22, v[104:107] offset:1024
	ds_write_b128 v23, v[108:111] offset:2048
	ds_write_b128 v24, v[112:115] offset:3072
	ds_write_b128 v25, v[116:119] offset:4096
	ds_write_b128 v26, v[120:123] offset:5120
	ds_write_b128 v27, v[124:127] offset:6144
	ds_write_b128 v28, v[128:131] offset:7168
	ds_read2_b32 v[100:101], v29 offset1:32
	ds_read2_b32 v[102:103], v29 offset0:64 offset1:96
	ds_read2_b32 v[104:105], v29 offset0:128 offset1:160
	ds_read2_b32 v[106:107], v29 offset0:192 offset1:224
	ds_read2_b32 v[108:109], v30 offset1:32
	ds_read2_b32 v[110:111], v30 offset0:64 offset1:96
	ds_read2_b32 v[112:113], v30 offset0:128 offset1:160
	ds_read2_b32 v[114:115], v30 offset0:192 offset1:224
	ds_read2_b32 v[116:117], v31 offset1:32
	ds_read2_b32 v[118:119], v31 offset0:64 offset1:96
	ds_read2_b32 v[120:121], v31 offset0:128 offset1:160
	ds_read2_b32 v[122:123], v31 offset0:192 offset1:224
	ds_read2_b32 v[124:125], v32 offset1:32
	ds_read2_b32 v[126:127], v32 offset0:64 offset1:96
	ds_read2_b32 v[128:129], v32 offset0:128 offset1:160
	ds_read2_b32 v[130:131], v32 offset0:192 offset1:224
	ds_bpermute_b32 v234, v12, v226
	ds_bpermute_b32 v235, v12, v227
	ds_bpermute_b32 v236, v12, v228
	ds_bpermute_b32 v237, v12, v229
	s_waitcnt lgkmcnt(4)
	v_cvt_pk_bf16_f32 v164, v100, v101
	v_cvt_pk_bf16_f32 v165, v102, v103
	v_cvt_pk_bf16_f32 v166, v104, v105
	v_cvt_pk_bf16_f32 v167, v106, v107
	v_cvt_pk_bf16_f32 v168, v108, v109
	v_cvt_pk_bf16_f32 v169, v110, v111
	v_cvt_pk_bf16_f32 v170, v112, v113
	v_cvt_pk_bf16_f32 v171, v114, v115
	v_cvt_pk_bf16_f32 v172, v116, v117
	v_cvt_pk_bf16_f32 v173, v118, v119
	v_cvt_pk_bf16_f32 v174, v120, v121
	v_cvt_pk_bf16_f32 v175, v122, v123
	v_cvt_pk_bf16_f32 v176, v124, v125
	v_cvt_pk_bf16_f32 v177, v126, v127
	v_cvt_pk_bf16_f32 v178, v128, v129
	v_cvt_pk_bf16_f32 v179, v130, v131
	s_waitcnt lgkmcnt(0)
	v_add_f32_e32 v226, v226, v234
	v_add_f32_e32 v227, v227, v235
	v_add_f32_e32 v228, v228, v236
	v_add_f32_e32 v229, v229, v237
	ds_bpermute_b32 v234, v13, v226
	ds_bpermute_b32 v235, v13, v227
	ds_bpermute_b32 v236, v13, v228
	ds_bpermute_b32 v237, v13, v229
	v_lshlrev_b32_e32 v238, 16, v164
	v_and_b32_e32 v239, s59, v164
	v_add_f32_e32 v230, v238, v239
	v_lshlrev_b32_e32 v238, 16, v165
	v_and_b32_e32 v239, s59, v165
	v_add_f32_e32 v230, v230, v238
	v_add_f32_e32 v230, v230, v239
	v_lshlrev_b32_e32 v238, 16, v166
	v_and_b32_e32 v239, s59, v166
	v_add_f32_e32 v230, v230, v238
	v_add_f32_e32 v230, v230, v239
	v_lshlrev_b32_e32 v238, 16, v167
	v_and_b32_e32 v239, s59, v167
	v_add_f32_e32 v230, v230, v238
	v_add_f32_e32 v230, v230, v239
	v_lshlrev_b32_e32 v238, 16, v168
	v_and_b32_e32 v239, s59, v168
	v_add_f32_e32 v231, v238, v239
	v_lshlrev_b32_e32 v238, 16, v169
	v_and_b32_e32 v239, s59, v169
	v_add_f32_e32 v231, v231, v238
	v_add_f32_e32 v231, v231, v239
	v_lshlrev_b32_e32 v238, 16, v170
	v_and_b32_e32 v239, s59, v170
	v_add_f32_e32 v231, v231, v238
	v_add_f32_e32 v231, v231, v239
	v_lshlrev_b32_e32 v238, 16, v171
	v_and_b32_e32 v239, s59, v171
	v_add_f32_e32 v231, v231, v238
	v_add_f32_e32 v231, v231, v239
	s_waitcnt lgkmcnt(0)
	v_add_f32_e32 v226, v226, v234
	v_add_f32_e32 v227, v227, v235
	v_add_f32_e32 v228, v228, v236
	v_add_f32_e32 v229, v229, v237
	ds_bpermute_b32 v234, v14, v226
	ds_bpermute_b32 v235, v14, v227
	ds_bpermute_b32 v236, v14, v228
	ds_bpermute_b32 v237, v14, v229
	v_lshlrev_b32_e32 v238, 16, v172
	v_and_b32_e32 v239, s59, v172
	v_add_f32_e32 v232, v238, v239
	v_lshlrev_b32_e32 v238, 16, v173
	v_and_b32_e32 v239, s59, v173
	v_add_f32_e32 v232, v232, v238
	v_add_f32_e32 v232, v232, v239
	v_lshlrev_b32_e32 v238, 16, v174
	v_and_b32_e32 v239, s59, v174
	v_add_f32_e32 v232, v232, v238
	v_add_f32_e32 v232, v232, v239
	v_lshlrev_b32_e32 v238, 16, v175
	v_and_b32_e32 v239, s59, v175
	v_add_f32_e32 v232, v232, v238
	v_add_f32_e32 v232, v232, v239
	v_lshlrev_b32_e32 v238, 16, v176
	v_and_b32_e32 v239, s59, v176
	v_add_f32_e32 v233, v238, v239
	v_lshlrev_b32_e32 v238, 16, v177
	v_and_b32_e32 v239, s59, v177
	v_add_f32_e32 v233, v233, v238
	v_add_f32_e32 v233, v233, v239
	v_lshlrev_b32_e32 v238, 16, v178
	v_and_b32_e32 v239, s59, v178
	v_add_f32_e32 v233, v233, v238
	v_add_f32_e32 v233, v233, v239
	v_lshlrev_b32_e32 v238, 16, v179
	v_and_b32_e32 v239, s59, v179
	v_add_f32_e32 v233, v233, v238
	v_add_f32_e32 v233, v233, v239
	s_nop 1
	v_add_f32_dpp v230, v230, v230 quad_perm:[1,0,3,2] row_mask:0xf bank_mask:0xf
	v_add_f32_dpp v231, v231, v231 quad_perm:[1,0,3,2] row_mask:0xf bank_mask:0xf
	v_add_f32_dpp v232, v232, v232 quad_perm:[1,0,3,2] row_mask:0xf bank_mask:0xf
	v_add_f32_dpp v233, v233, v233 quad_perm:[1,0,3,2] row_mask:0xf bank_mask:0xf
	v_add_f32_dpp v230, v230, v230 quad_perm:[2,3,0,1] row_mask:0xf bank_mask:0xf
	v_add_f32_dpp v231, v231, v231 quad_perm:[2,3,0,1] row_mask:0xf bank_mask:0xf
	v_add_f32_dpp v232, v232, v232 quad_perm:[2,3,0,1] row_mask:0xf bank_mask:0xf
	v_add_f32_dpp v233, v233, v233 quad_perm:[2,3,0,1] row_mask:0xf bank_mask:0xf
	v_add_f32_dpp v230, v230, v230 row_half_mirror row_mask:0xf bank_mask:0xf
	v_add_f32_dpp v231, v231, v231 row_half_mirror row_mask:0xf bank_mask:0xf
	v_add_f32_dpp v232, v232, v232 row_half_mirror row_mask:0xf bank_mask:0xf
	v_add_f32_dpp v233, v233, v233 row_half_mirror row_mask:0xf bank_mask:0xf
	s_waitcnt lgkmcnt(0)
	v_add_f32_e32 v226, v226, v234
	v_add_f32_e32 v227, v227, v235
	v_add_f32_e32 v228, v228, v236
	v_add_f32_e32 v229, v229, v237
	global_store_dwordx4 v17, v[164:167], s[36:37]
	global_store_dwordx4 v18, v[168:171], s[36:37]
	global_store_dwordx4 v19, v[172:175], s[36:37]
	global_store_dwordx4 v20, v[176:179], s[36:37]
	s_add_u32 s48, s38, s40
	s_addc_u32 s49, s39, 0
	s_mov_b64 exec, s[56:57]
	global_atomic_add_f32 v15, v230, s[38:39]
	global_atomic_add_f32 v15, v231, s[38:39] offset:32
	global_atomic_add_f32 v15, v232, s[38:39] offset:64
	global_atomic_add_f32 v15, v233, s[38:39] offset:96
	s_mov_b64 exec, s[64:65]
	global_atomic_add_f32 v16, v226, s[48:49]
	global_atomic_add_f32 v16, v227, s[48:49] offset:4
	global_atomic_add_f32 v16, v228, s[48:49] offset:8
	global_atomic_add_f32 v16, v229, s[48:49] offset:12
	s_mov_b64 exec, -1
	s_cmp_lt_u32 s30, 0x4000
	s_cbranch_scc1 .Lgv5_w1
	s_cmp_lt_u32 s30, 0x5000
	s_cbranch_scc1 .Lgv5_pg
	s_cmp_lt_u32 s30, 0x5800
	s_cbranch_scc1 .Lgv5_wq
	s_cmp_lt_u32 s30, 0x5a00
	s_cbranch_scc1 .Lgv5_wk
	s_cmp_lt_u32 s30, 0x5c00
	s_cbranch_scc1 .Lgv5_wv
	s_mov_b32 s12, 0
	s_load_dwordx2 s[4:5], s[18:19], 0x98
	s_load_dwordx2 s[6:7], s[18:19], 0x100
	s_load_dwordx2 s[8:9], s[18:19], 0x108
	s_mov_b32 s10, 11
	s_mov_b32 s11, 4
	s_mov_b32 s69, 0x2d200000
	s_mov_b32 s70, 0x2e200000
	s_mov_b32 s40, 0x3000
	s_mov_b32 s71, 0
	s_mov_b32 s72, 0
	s_branch .Lgv5_common

.Lgv5_common:
	s_lshr_b32 s13, s12, s11
	s_lshl_b32 s15, s13, s11
	s_sub_i32 s14, s12, s15
	s_add_i32 s15, s10, 6
	s_lshl_b32 s15, s13, s15
	s_lshl_b32 s21, s14, 7
	s_add_i32 s15, s15, s21
	s_lshl_b32 s29, 8, s10
	v_lshlrev_b32_e32 v4, s10, v2
	v_lshl_add_u32 v4, v3, 4, v4
	s_lshl_b32 s21, s13, 8
	s_waitcnt lgkmcnt(0)
	s_add_u32 s4, s4, s71
	s_addc_u32 s5, s5, 0
	s_add_u32 s4, s4, s15
	s_addc_u32 s5, s5, 0
	s_add_u32 s6, s6, s72
	s_addc_u32 s7, s7, 0
	s_add_u32 s6, s6, s21
	s_addc_u32 s7, s7, 0
	s_add_u32 s8, s8, s72
	s_addc_u32 s9, s9, 0
	s_add_u32 s8, s8, s21
	s_addc_u32 s9, s9, 0
	global_load_dwordx4 v[100:103], v4, s[4:5] nt
	s_add_u32 s4, s4, s29
	s_addc_u32 s5, s5, 0
	global_load_dwordx4 v[104:107], v4, s[4:5] nt
	s_add_u32 s4, s4, s29
	s_addc_u32 s5, s5, 0
	global_load_dwordx4 v[108:111], v4, s[4:5] nt
	s_add_u32 s4, s4, s29
	s_addc_u32 s5, s5, 0
	global_load_dwordx4 v[112:115], v4, s[4:5] nt
	s_add_u32 s4, s4, s29
	s_addc_u32 s5, s5, 0
	global_load_dwordx4 v[116:119], v4, s[4:5] nt
	s_add_u32 s4, s4, s29
	s_addc_u32 s5, s5, 0
	global_load_dwordx4 v[120:123], v4, s[4:5] nt
	s_add_u32 s4, s4, s29
	s_addc_u32 s5, s5, 0
	global_load_dwordx4 v[124:127], v4, s[4:5] nt
	s_add_u32 s4, s4, s29
	s_addc_u32 s5, s5, 0
	global_load_dwordx4 v[128:131], v4, s[4:5] nt
	global_load_dword v206, v5, s[6:7]
	global_load_dword v207, v5, s[8:9]
	s_lshl_b32 s15, s14, 17
	s_lshl_b32 s21, s13, 7
	s_add_i32 s15, s15, s21
	s_add_u32 s36, s16, s69
	s_addc_u32 s37, s17, 0
	s_add_u32 s36, s36, s15
	s_addc_u32 s37, s37, 0
	s_lshl_b32 s15, s14, 7
	s_add_u32 s38, s16, s70
	s_addc_u32 s39, s17, 0
	s_add_u32 s38, s38, s15
	s_addc_u32 s39, s39, 0
	s_addk_i32 s30, 0x800
	s_add_i32 s3, s3, -1
	s_cmp_lg_u32 s3, 0
	s_cbranch_scc1 .Lgv_loop
	s_waitcnt vmcnt(22)
	ds_write_b32 v10, v208
	ds_write_b32 v10, v209 offset:256
	ds_read_b128 v[210:213], v11
	ds_read_b128 v[214:217], v11 offset:16
	ds_read_b128 v[218:221], v11 offset:256
	ds_read_b128 v[222:225], v11 offset:272
	s_waitcnt lgkmcnt(0)
	v_mul_f32_e32 v226, v132, v218
	v_mul_f32_e32 v132, v132, v210
	v_mul_f32_e32 v227, v133, v218
	v_mul_f32_e32 v133, v133, v210
	v_mul_f32_e32 v228, v134, v218
	v_mul_f32_e32 v134, v134, v210
	v_mul_f32_e32 v229, v135, v218
	v_mul_f32_e32 v135, v135, v210
	v_fmac_f32_e32 v226, v136, v219
	v_mul_f32_e32 v136, v136, v211
	v_fmac_f32_e32 v227, v137, v219
	v_mul_f32_e32 v137, v137, v211
	v_fmac_f32_e32 v228, v138, v219
	v_mul_f32_e32 v138, v138, v211
	v_fmac_f32_e32 v229, v139, v219
	v_mul_f32_e32 v139, v139, v211
	v_fmac_f32_e32 v226, v140, v220
	v_mul_f32_e32 v140, v140, v212
	v_fmac_f32_e32 v227, v141, v220
	v_mul_f32_e32 v141, v141, v212
	v_fmac_f32_e32 v228, v142, v220
	v_mul_f32_e32 v142, v142, v212
	v_fmac_f32_e32 v229, v143, v220
	v_mul_f32_e32 v143, v143, v212
	v_fmac_f32_e32 v226, v144, v221
	v_mul_f32_e32 v144, v144, v213
	v_fmac_f32_e32 v227, v145, v221
	v_mul_f32_e32 v145, v145, v213
	v_fmac_f32_e32 v228, v146, v221
	v_mul_f32_e32 v146, v146, v213
	v_fmac_f32_e32 v229, v147, v221
	v_mul_f32_e32 v147, v147, v213
	v_fmac_f32_e32 v226, v148, v222
	v_mul_f32_e32 v148, v148, v214
	v_fmac_f32_e32 v227, v149, v222
	v_mul_f32_e32 v149, v149, v214
	v_fmac_f32_e32 v228, v150, v222
	v_mul_f32_e32 v150, v150, v214
	v_fmac_f32_e32 v229, v151, v222
	v_mul_f32_e32 v151, v151, v214
	v_fmac_f32_e32 v226, v152, v223
	v_mul_f32_e32 v152, v152, v215
	v_fmac_f32_e32 v227, v153, v223
	v_mul_f32_e32 v153, v153, v215
	v_fmac_f32_e32 v228, v154, v223
	v_mul_f32_e32 v154, v154, v215
	v_fmac_f32_e32 v229, v155, v223
	v_mul_f32_e32 v155, v155, v215
	v_fmac_f32_e32 v226, v156, v224
	v_mul_f32_e32 v156, v156, v216
	v_fmac_f32_e32 v227, v157, v224
	v_mul_f32_e32 v157, v157, v216
	v_fmac_f32_e32 v228, v158, v224
	v_mul_f32_e32 v158, v158, v216
	v_fmac_f32_e32 v229, v159, v224
	v_mul_f32_e32 v159, v159, v216
	v_fmac_f32_e32 v226, v160, v225
	v_mul_f32_e32 v160, v160, v217
	v_fmac_f32_e32 v227, v161, v225
	v_mul_f32_e32 v161, v161, v217
	v_fmac_f32_e32 v228, v162, v225
	v_mul_f32_e32 v162, v162, v217
	v_fmac_f32_e32 v229, v163, v225
	v_mul_f32_e32 v163, v163, v217
	ds_write_b128 v21, v[132:135]
	ds_write_b128 v22, v[136:139] offset:1024
	ds_write_b128 v23, v[140:143] offset:2048
	ds_write_b128 v24, v[144:147] offset:3072
	ds_write_b128 v25, v[148:151] offset:4096
	ds_write_b128 v26, v[152:155] offset:5120
	ds_write_b128 v27, v[156:159] offset:6144
	ds_write_b128 v28, v[160:163] offset:7168
	ds_read2_b32 v[132:133], v29 offset1:32
	ds_read2_b32 v[134:135], v29 offset0:64 offset1:96
	ds_read2_b32 v[136:137], v29 offset0:128 offset1:160
	ds_read2_b32 v[138:139], v29 offset0:192 offset1:224
	ds_read2_b32 v[140:141], v30 offset1:32
	ds_read2_b32 v[142:143], v30 offset0:64 offset1:96
	ds_read2_b32 v[144:145], v30 offset0:128 offset1:160
	ds_read2_b32 v[146:147], v30 offset0:192 offset1:224
	ds_read2_b32 v[148:149], v31 offset1:32
	ds_read2_b32 v[150:151], v31 offset0:64 offset1:96
	ds_read2_b32 v[152:153], v31 offset0:128 offset1:160
	ds_read2_b32 v[154:155], v31 offset0:192 offset1:224
	ds_read2_b32 v[156:157], v32 offset1:32
	ds_read2_b32 v[158:159], v32 offset0:64 offset1:96
	ds_read2_b32 v[160:161], v32 offset0:128 offset1:160
	ds_read2_b32 v[162:163], v32 offset0:192 offset1:224
	ds_bpermute_b32 v234, v12, v226
	ds_bpermute_b32 v235, v12, v227
	ds_bpermute_b32 v236, v12, v228
	ds_bpermute_b32 v237, v12, v229
	s_waitcnt lgkmcnt(4)
	v_cvt_pk_bf16_f32 v190, v132, v133
	v_cvt_pk_bf16_f32 v191, v134, v135
	v_cvt_pk_bf16_f32 v192, v136, v137
	v_cvt_pk_bf16_f32 v193, v138, v139
	v_cvt_pk_bf16_f32 v194, v140, v141
	v_cvt_pk_bf16_f32 v195, v142, v143
	v_cvt_pk_bf16_f32 v196, v144, v145
	v_cvt_pk_bf16_f32 v197, v146, v147
	v_cvt_pk_bf16_f32 v198, v148, v149
	v_cvt_pk_bf16_f32 v199, v150, v151
	v_cvt_pk_bf16_f32 v200, v152, v153
	v_cvt_pk_bf16_f32 v201, v154, v155
	v_cvt_pk_bf16_f32 v202, v156, v157
	v_cvt_pk_bf16_f32 v203, v158, v159
	v_cvt_pk_bf16_f32 v204, v160, v161
	v_cvt_pk_bf16_f32 v205, v162, v163
	s_waitcnt lgkmcnt(0)
	v_add_f32_e32 v226, v226, v234
	v_add_f32_e32 v227, v227, v235
	v_add_f32_e32 v228, v228, v236
	v_add_f32_e32 v229, v229, v237
	ds_bpermute_b32 v234, v13, v226
	ds_bpermute_b32 v235, v13, v227
	ds_bpermute_b32 v236, v13, v228
	ds_bpermute_b32 v237, v13, v229
	v_lshlrev_b32_e32 v238, 16, v190
	v_and_b32_e32 v239, s59, v190
	v_add_f32_e32 v230, v238, v239
	v_lshlrev_b32_e32 v238, 16, v191
	v_and_b32_e32 v239, s59, v191
	v_add_f32_e32 v230, v230, v238
	v_add_f32_e32 v230, v230, v239
	v_lshlrev_b32_e32 v238, 16, v192
	v_and_b32_e32 v239, s59, v192
	v_add_f32_e32 v230, v230, v238
	v_add_f32_e32 v230, v230, v239
	v_lshlrev_b32_e32 v238, 16, v193
	v_and_b32_e32 v239, s59, v193
	v_add_f32_e32 v230, v230, v238
	v_add_f32_e32 v230, v230, v239
	v_lshlrev_b32_e32 v238, 16, v194
	v_and_b32_e32 v239, s59, v194
	v_add_f32_e32 v231, v238, v239
	v_lshlrev_b32_e32 v238, 16, v195
	v_and_b32_e32 v239, s59, v195
	v_add_f32_e32 v231, v231, v238
	v_add_f32_e32 v231, v231, v239
	v_lshlrev_b32_e32 v238, 16, v196
	v_and_b32_e32 v239, s59, v196
	v_add_f32_e32 v231, v231, v238
	v_add_f32_e32 v231, v231, v239
	v_lshlrev_b32_e32 v238, 16, v197
	v_and_b32_e32 v239, s59, v197
	v_add_f32_e32 v231, v231, v238
	v_add_f32_e32 v231, v231, v239
	s_waitcnt lgkmcnt(0)
	v_add_f32_e32 v226, v226, v234
	v_add_f32_e32 v227, v227, v235
	v_add_f32_e32 v228, v228, v236
	v_add_f32_e32 v229, v229, v237
	ds_bpermute_b32 v234, v14, v226
	ds_bpermute_b32 v235, v14, v227
	ds_bpermute_b32 v236, v14, v228
	ds_bpermute_b32 v237, v14, v229
	v_lshlrev_b32_e32 v238, 16, v198
	v_and_b32_e32 v239, s59, v198
	v_add_f32_e32 v232, v238, v239
	v_lshlrev_b32_e32 v238, 16, v199
	v_and_b32_e32 v239, s59, v199
	v_add_f32_e32 v232, v232, v238
	v_add_f32_e32 v232, v232, v239
	v_lshlrev_b32_e32 v238, 16, v200
	v_and_b32_e32 v239, s59, v200
	v_add_f32_e32 v232, v232, v238
	v_add_f32_e32 v232, v232, v239
	v_lshlrev_b32_e32 v238, 16, v201
	v_and_b32_e32 v239, s59, v201
	v_add_f32_e32 v232, v232, v238
	v_add_f32_e32 v232, v232, v239
	v_lshlrev_b32_e32 v238, 16, v202
	v_and_b32_e32 v239, s59, v202
	v_add_f32_e32 v233, v238, v239
	v_lshlrev_b32_e32 v238, 16, v203
	v_and_b32_e32 v239, s59, v203
	v_add_f32_e32 v233, v233, v238
	v_add_f32_e32 v233, v233, v239
	v_lshlrev_b32_e32 v238, 16, v204
	v_and_b32_e32 v239, s59, v204
	v_add_f32_e32 v233, v233, v238
	v_add_f32_e32 v233, v233, v239
	v_lshlrev_b32_e32 v238, 16, v205
	v_and_b32_e32 v239, s59, v205
	v_add_f32_e32 v233, v233, v238
	v_add_f32_e32 v233, v233, v239
	s_nop 1
	v_add_f32_dpp v230, v230, v230 quad_perm:[1,0,3,2] row_mask:0xf bank_mask:0xf
	v_add_f32_dpp v231, v231, v231 quad_perm:[1,0,3,2] row_mask:0xf bank_mask:0xf
	v_add_f32_dpp v232, v232, v232 quad_perm:[1,0,3,2] row_mask:0xf bank_mask:0xf
	v_add_f32_dpp v233, v233, v233 quad_perm:[1,0,3,2] row_mask:0xf bank_mask:0xf
	v_add_f32_dpp v230, v230, v230 quad_perm:[2,3,0,1] row_mask:0xf bank_mask:0xf
	v_add_f32_dpp v231, v231, v231 quad_perm:[2,3,0,1] row_mask:0xf bank_mask:0xf
	v_add_f32_dpp v232, v232, v232 quad_perm:[2,3,0,1] row_mask:0xf bank_mask:0xf
	v_add_f32_dpp v233, v233, v233 quad_perm:[2,3,0,1] row_mask:0xf bank_mask:0xf
	v_add_f32_dpp v230, v230, v230 row_half_mirror row_mask:0xf bank_mask:0xf
	v_add_f32_dpp v231, v231, v231 row_half_mirror row_mask:0xf bank_mask:0xf
	v_add_f32_dpp v232, v232, v232 row_half_mirror row_mask:0xf bank_mask:0xf
	v_add_f32_dpp v233, v233, v233 row_half_mirror row_mask:0xf bank_mask:0xf
	s_waitcnt lgkmcnt(0)
	v_add_f32_e32 v226, v226, v234
	v_add_f32_e32 v227, v227, v235
	v_add_f32_e32 v228, v228, v236
	v_add_f32_e32 v229, v229, v237
	global_store_dwordx4 v17, v[190:193], s[42:43]
	global_store_dwordx4 v18, v[194:197], s[42:43]
	global_store_dwordx4 v19, v[198:201], s[42:43]
	global_store_dwordx4 v20, v[202:205], s[42:43]
	s_add_u32 s48, s44, s47
	s_addc_u32 s49, s45, 0
	s_mov_b64 exec, s[56:57]
	global_atomic_add_f32 v15, v230, s[44:45]
	global_atomic_add_f32 v15, v231, s[44:45] offset:32
	global_atomic_add_f32 v15, v232, s[44:45] offset:64
	global_atomic_add_f32 v15, v233, s[44:45] offset:96
	s_mov_b64 exec, s[64:65]
	global_atomic_add_f32 v16, v226, s[48:49]
	global_atomic_add_f32 v16, v227, s[48:49] offset:4
	global_atomic_add_f32 v16, v228, s[48:49] offset:8
	global_atomic_add_f32 v16, v229, s[48:49] offset:12
	s_mov_b64 exec, -1
	s_waitcnt vmcnt(0) lgkmcnt(0)
	s_lshl_b32 s8, s85, 14
	v_and_b32_e32 v1, 7, v0
	v_lshrrev_b32_e32 v7, 3, v244
	s_add_i32 s3, s8, 0
	v_mul_u32_u24_e32 v4, 0x420, v1
	v_lshlrev_b32_e32 v9, 2, v7
	v_and_b32_e32 v32, 31, v0
	v_mov_b32_e32 v5, 0
	v_add3_u32 v9, s3, v4, v9
	v_lshlrev_b32_e32 v4, 4, v1
	v_lshlrev_b32_e32 v34, 2, v32
	s_waitcnt lgkmcnt(0)
	v_lshl_add_u64 v[28:29], s[16:17], 0, v[4:5]
	s_mov_b64 s[6:7], 0x6700000
	v_mov_b32_e32 v35, v5
	v_lshl_add_u64 v[10:11], v[28:29], 0, s[6:7]
	v_lshl_add_u64 v[24:25], s[16:17], 0, v[34:35]
	s_mov_b64 s[6:7], 0x195000
	v_lshl_add_u64 v[12:13], v[24:25], 0, s[6:7]
	s_mov_b64 s[6:7], 0x198000
	v_lshl_add_u64 v[14:15], v[24:25], 0, s[6:7]
	s_mov_b64 s[6:7], 0x5b00000
	v_lshl_add_u64 v[16:17], v[28:29], 0, s[6:7]
	s_mov_b64 s[6:7], 0x194800
	v_lshl_add_u64 v[18:19], v[24:25], 0, s[6:7]
	s_mov_b64 s[6:7], 0x197800
	v_lshl_add_u64 v[20:21], v[24:25], 0, s[6:7]
	s_mov_b64 s[6:7], 0x194000
	v_lshl_add_u64 v[22:23], v[24:25], 0, s[6:7]
	s_mov_b64 s[6:7], 0x197000
	v_lshl_add_u64 v[24:25], v[24:25], 0, s[6:7]
	s_mov_b64 s[6:7], 0xa00000
	v_bfe_u32 v4, v0, 5, 1
	v_lshl_add_u64 v[26:27], v[28:29], 0, s[6:7]
	s_mov_b64 s[6:7], 0x200000
	v_lshlrev_b32_e32 v30, 7, v4
	v_mul_u32_u24_e32 v4, 0x1080, v4
	s_add_u32 s0, s16, 0x180000
	v_lshl_add_u64 v[28:29], v[28:29], 0, s[6:7]
	v_readlane_b32 s6, v255, 8
	v_or3_b32 v4, s8, v4, v34
	s_addc_u32 s1, s17, 0
	v_lshrrev_b32_e32 v2, 5, v244
	v_add_u32_e32 v6, s3, v34
	s_mov_b32 s10, s6
	s_add_i32 s3, s6, 0x9b00
	v_add_u32_e32 v47, 0, v4
	s_add_i32 s30, s6, 0xec00
	s_lshl_b32 s6, s6, 2
	v_mbcnt_lo_u32_b32 v4, -1, 0
	s_mov_b32 s21, 0
	v_and_b32_e32 v3, 32, v0
	v_cmp_gt_u32_e64 s[4:5], 32, v244
	v_lshlrev_b32_e32 v8, 3, v1
	v_or_b32_e32 v44, 8, v7
	v_or_b32_e32 v45, 16, v7
	v_or_b32_e32 v46, 24, v7
	v_mov_b32_e32 v1, v2
	v_mov_b32_e32 v31, v5
	s_add_i32 s31, s6, 0x3b800
	s_lshl_b32 s33, s94, 5
	s_add_i32 s36, s6, 0x3c000
	s_movk_i32 s37, 0x84
	s_movk_i32 s38, 0x7fff
	s_mov_b32 s39, 0xffff0000
	s_mov_b32 s40, 0x10000
	s_mov_b32 s41, 0x5300000
	s_mov_b32 s42, 0x5200000
	s_mov_b32 s43, 0x3200000
	s_mov_b32 s44, 0x1200000
	v_lshlrev_b32_e32 v32, 2, v32
	v_mbcnt_hi_u32_b32 v48, -1, v4
	s_mov_b32 s45, s10
	v_readlane_b32 s7, v255, 9
	s_branch .LBB0_19

.LBB0_19:
	s_cmpk_gt_i32 s45, 0x7ff
	s_mov_b64 s[6:7], -1
	s_cbranch_scc0 .LBB0_181
	s_cmpk_gt_u32 s45, 0xfff
	s_cbranch_scc0 .LBB0_176
	s_waitcnt lgkmcnt(0)
	s_load_dwordx4 s[8:11], s[18:19], 0x100
	s_cmpk_gt_u32 s45, 0x11ff
	s_cbranch_scc0 .LBB0_149
	s_cmpk_gt_u32 s45, 0x13ff
	s_cbranch_scc0 .LBB0_122
	s_cmpk_gt_u32 s45, 0x1bff
	s_cbranch_scc0 .LBB0_95
	s_add_i32 s46, s45, 0xffffe400
	s_cmpk_gt_u32 s46, 0x7ff
	s_cbranch_scc0 .LBB0_90
	s_add_i32 s28, s45, 0xffffdc00
	s_cmpk_gt_u32 s28, 0x48ff
	s_cselect_b64 s[22:23], -1, 0
	s_and_b64 s[6:7], s[22:23], exec
	s_cselect_b32 s20, 0xffffb700, 0
	s_add_i32 s29, s20, s28
	s_cmpk_gt_i32 s29, 0x1fff
	s_mov_b64 s[6:7], -1
	s_cbranch_scc0 .LBB0_63
	s_cmpk_gt_u32 s29, 0x3fff
	s_cbranch_scc0 .LBB0_58
	s_cmpk_gt_u32 s29, 0x40ff
	s_cbranch_scc0 .LBB0_53
	s_mov_b64 s[6:7], 0
	s_branch .LBB0_53
	s_load_dwordx4 s[12:15], s[18:19], 0xe0
	s_load_dwordx2 s[24:25], s[18:19], 0xf8
	s_and_b64 s[26:27], s[22:23], exec
	s_cselect_b32 s49, 0x800, 0
	s_lshl_b32 s7, s49, 13
	v_mov_b32_e32 v33, v5
	s_waitcnt lgkmcnt(0)
	s_add_u32 s7, s24, s7
	s_addc_u32 s25, s25, 0
	s_add_i32 s24, s29, 0xbf00
	s_and_b32 s48, s24, 0xffc0
	s_lshl_b32 s24, s45, 5
	s_and_b32 s47, s24, 0x7e0
	s_lshl_b32 s24, s47, 2
	s_add_u32 s24, s7, s24
	s_addc_u32 s25, s25, 0
	s_mov_b32 s6, 0
	v_lshl_add_u64 v[34:35], s[24:25], 0, v[32:33]
	s_mov_b32 s7, s48
	s_mov_b32 s24, 1
	s_mov_b32 s25, 32

.LBB0_63:
	s_andn2_b64 vcc, exec, s[6:7]
	s_cbranch_vccnz .LBB0_89
	s_branch .LBB0_89
	s_load_dwordx4 s[12:15], s[18:19], 0xc0
	s_load_dwordx2 s[6:7], s[18:19], 0xd0
	s_and_b64 s[22:23], s[22:23], exec
	s_cselect_b32 s47, 0x800, 0
	s_lshl_b32 s22, s47, 15
	v_mov_b32_e32 v33, v5
	s_waitcnt lgkmcnt(0)
	s_add_u32 s25, s6, s22
	s_sext_i32_i16 s6, s29
	s_addc_u32 s27, s7, 0
	s_bfe_u32 s6, s6, 0x80017
	s_add_i32 s6, s29, s6
	s_sext_i32_i16 s7, s6
	s_and_b32 s6, s6, 0xff00
	s_sub_i32 s6, s29, s6
	s_sext_i32_i16 s6, s6
	s_lshl_b32 s22, s6, 5
	s_ashr_i32 s7, s7, 8
	s_ashr_i32 s23, s22, 31
	s_lshl_b32 s24, s7, 6
	s_lshl_b64 s[6:7], s[22:23], 2
	s_add_u32 s26, s25, s6
	s_addc_u32 s27, s27, s7
	s_mov_b32 s20, 0
	v_lshl_add_u64 v[34:35], s[26:27], 0, v[32:33]
	s_mov_b32 s23, s24
	s_mov_b32 s25, 1
	s_mov_b32 s26, 32

.LBB0_95:
	s_andn2_b64 vcc, exec, s[6:7]
	s_cbranch_vccnz .LBB0_121
	s_branch .LBB0_121
	s_load_dwordx2 s[6:7], s[18:19], 0xa8
	s_add_i32 s12, s45, 0xec00
	s_and_b32 s14, s12, 0xffc0
	s_lshl_b32 s12, s45, 5
	s_and_b32 s15, s12, 0x7e0
	s_lshl_b32 s12, s15, 2
	s_waitcnt lgkmcnt(0)
	s_add_u32 s6, s6, s12
	s_addc_u32 s7, s7, 0
	v_mov_b32_e32 v33, v5
	v_lshl_add_u64 v[34:35], s[6:7], 0, v[32:33]
	s_mov_b32 s6, s14
	s_mov_b32 s7, 1
	s_mov_b32 s12, 0
	s_mov_b32 s13, 32

.LBB0_122:
	s_andn2_b64 vcc, exec, s[6:7]
	s_cbranch_vccnz .LBB0_148
	s_branch .LBB0_148
	s_load_dwordx2 s[6:7], s[18:19], 0xa0
	s_lshl_b32 s12, s45, 2
	s_add_i32 s12, s12, 0x3b800
	s_and_b32 s14, s12, 0x3ffc0
	s_lshl_b32 s12, s45, 5
	s_and_b32 s15, s12, 0x1e0
	s_lshl_b32 s12, s15, 2
	s_waitcnt lgkmcnt(0)
	s_add_u32 s6, s6, s12
	s_addc_u32 s7, s7, 0
	v_mov_b32_e32 v33, v5
	v_lshl_add_u64 v[34:35], s[6:7], 0, v[32:33]
	s_mov_b32 s6, s14
	s_mov_b32 s7, 1
	s_mov_b32 s12, 0
	s_mov_b32 s13, 32

.LBB0_149:
	s_andn2_b64 vcc, exec, s[6:7]
	s_cbranch_vccnz .LBB0_175
	s_branch .LBB0_175
	s_load_dwordx2 s[6:7], s[18:19], 0x98
	s_lshl_b32 s12, s45, 2
	s_add_i32 s12, s12, 0x3c000
	s_and_b32 s15, s12, 0x3ffc0
	s_lshl_b32 s12, s45, 5
	s_and_b32 s14, s12, 0x1e0
	s_lshl_b32 s12, s14, 2
	s_waitcnt lgkmcnt(0)
	s_add_u32 s6, s6, s12
	s_addc_u32 s7, s7, 0
	v_mov_b32_e32 v33, v5
	v_lshl_add_u64 v[34:35], s[6:7], 0, v[32:33]
	s_mov_b32 s6, s15
	s_mov_b32 s7, 1
	s_mov_b32 s12, 0
	s_mov_b32 s13, 32
